# main GEMM fast epilogues keep store data in registers the k-loop never writes; no vmcnt drain before the next unit's k-loop
# baseline (speedup 1.0000x reference)
.LBB0_372:
	s_add_u32 s8, s6, 0xfff80080
	s_addc_u32 s9, s7, -1
	s_add_i32 s21, 0, 0x10000
	v_add_u32_e32 v143, s21, v167
	ds_read_b128 v[148:151], v143
	ds_read_b128 v[152:155], v143 offset:1024
	ds_read_b128 v[156:159], v143 offset:2048
	ds_read_b128 v[160:163], v143 offset:3072
	s_cmp_eq_u32 s20, 28
	s_cselect_b32 s11, s17, s9
	s_cselect_b32 s10, s16, s8
	s_cselect_b32 s9, s19, s15
	s_cselect_b32 s8, s18, s13
	s_add_i32 s24, 0, 0x14000
	v_add_u32_e32 v143, s24, v167
	ds_read_b128 v[208:211], v143
	ds_read_b128 v[212:215], v143 offset:1024
	ds_read_b128 v[216:219], v143 offset:2048
	ds_read_b128 v[220:223], v143 offset:3072
	v_lshl_add_u64 v[164:165], s[6:7], 0, v[138:139]
	s_add_i32 m0, s40, 0xc000
	ds_read_b128 v[172:175], v171
	ds_read_b128 v[180:183], v171 offset:1024
	ds_read_b128 v[184:187], v171 offset:2048
	ds_read_b128 v[188:191], v171 offset:3072
	ds_read_b128 v[192:195], v171 offset:4096
	ds_read_b128 v[196:199], v171 offset:5120
	ds_read_b128 v[200:203], v171 offset:6144
	ds_read_b128 v[204:207], v171 offset:7168
	global_load_lds_dwordx4 v[164:165], off
	v_lshl_add_u64 v[164:165], s[6:7], 0, v[140:141]
	s_add_i32 m0, s40, 0xe000
	s_nop 0
	global_load_lds_dwordx4 v[164:165], off
	s_waitcnt lgkmcnt(0)
	s_barrier
	s_setprio 1
	v_mfma_f32_16x16x32_bf16 v[126:129], v[148:151], v[172:175], v[126:129]
	v_mfma_f32_16x16x32_bf16 v[122:125], v[156:159], v[172:175], v[122:125]
	v_mfma_f32_16x16x32_bf16 v[110:113], v[148:151], v[184:187], v[110:113]
	v_mfma_f32_16x16x32_bf16 v[106:109], v[156:159], v[184:187], v[106:109]
	v_mfma_f32_16x16x32_bf16 v[94:97], v[148:151], v[192:195], v[94:97]
	v_mfma_f32_16x16x32_bf16 v[90:93], v[156:159], v[192:195], v[90:93]
	v_mfma_f32_16x16x32_bf16 v[78:81], v[148:151], v[200:203], v[78:81]
	v_mfma_f32_16x16x32_bf16 v[74:77], v[156:159], v[200:203], v[74:77]
	v_mfma_f32_16x16x32_bf16 v[126:129], v[152:155], v[180:183], v[126:129]
	v_mfma_f32_16x16x32_bf16 v[122:125], v[160:163], v[180:183], v[122:125]
	v_mfma_f32_16x16x32_bf16 v[110:113], v[152:155], v[188:191], v[110:113]
	v_mfma_f32_16x16x32_bf16 v[106:109], v[160:163], v[188:191], v[106:109]
	v_mfma_f32_16x16x32_bf16 v[94:97], v[152:155], v[196:199], v[94:97]
	v_mfma_f32_16x16x32_bf16 v[90:93], v[160:163], v[196:199], v[90:93]
	v_mfma_f32_16x16x32_bf16 v[78:81], v[152:155], v[204:207], v[78:81]
	v_mfma_f32_16x16x32_bf16 v[74:77], v[160:163], v[204:207], v[74:77]
	v_mfma_f32_16x16x32_bf16 v[118:121], v[208:211], v[172:175], v[118:121]
	v_mfma_f32_16x16x32_bf16 v[114:117], v[216:219], v[172:175], v[114:117]
	v_mfma_f32_16x16x32_bf16 v[102:105], v[208:211], v[184:187], v[102:105]
	v_mfma_f32_16x16x32_bf16 v[98:101], v[216:219], v[184:187], v[98:101]
	v_mfma_f32_16x16x32_bf16 v[86:89], v[208:211], v[192:195], v[86:89]
	v_mfma_f32_16x16x32_bf16 v[82:85], v[216:219], v[192:195], v[82:85]
	v_mfma_f32_16x16x32_bf16 v[70:73], v[208:211], v[200:203], v[70:73]
	v_mfma_f32_16x16x32_bf16 v[66:69], v[216:219], v[200:203], v[66:69]
	v_mfma_f32_16x16x32_bf16 v[118:121], v[212:215], v[180:183], v[118:121]
	v_mfma_f32_16x16x32_bf16 v[114:117], v[220:223], v[180:183], v[114:117]
	v_mfma_f32_16x16x32_bf16 v[102:105], v[212:215], v[188:191], v[102:105]
	v_mfma_f32_16x16x32_bf16 v[98:101], v[220:223], v[188:191], v[98:101]
	v_mfma_f32_16x16x32_bf16 v[86:89], v[212:215], v[196:199], v[86:89]
	v_mfma_f32_16x16x32_bf16 v[82:85], v[220:223], v[196:199], v[82:85]
	v_mfma_f32_16x16x32_bf16 v[70:73], v[212:215], v[204:207], v[70:73]
	v_mfma_f32_16x16x32_bf16 v[66:69], v[220:223], v[204:207], v[66:69]
	s_setprio 0
	s_mov_b32 m0, s40
	v_lshl_add_u64 v[224:225], s[10:11], 0, v[136:137]
	s_barrier
	ds_read_b128 v[172:175], v171 offset:16384
	ds_read_b128 v[180:183], v171 offset:17408
	ds_read_b128 v[184:187], v171 offset:18432
	ds_read_b128 v[188:191], v171 offset:19456
	ds_read_b128 v[192:195], v171 offset:20480
	ds_read_b128 v[196:199], v171 offset:21504
	ds_read_b128 v[200:203], v171 offset:22528
	ds_read_b128 v[204:207], v171 offset:23552
	s_add_i32 s21, s21, s39
	v_lshl_add_u64 v[164:165], s[8:9], 0, v[134:135]
	s_mov_b32 m0, s21
	s_nop 0
	global_load_lds_dwordx4 v[164:165], off
	v_lshl_add_u64 v[176:177], s[8:9], 0, v[130:131]
	s_add_i32 m0, s21, 0x2000
	s_nop 0
	global_load_lds_dwordx4 v[176:177], off
	s_mov_b32 m0, s40
	s_nop 0
	global_load_lds_dwordx4 v[224:225], off
	v_lshl_add_u64 v[236:237], s[10:11], 0, v[132:133]
	s_mov_b32 m0, s41
	s_nop 0
	global_load_lds_dwordx4 v[236:237], off
	s_add_u32 s22, s8, 0x80000
	s_addc_u32 s23, s9, 0
	s_add_i32 s21, s24, s39
	s_mov_b32 m0, s21
	s_nop 0
	global_load_lds_dwordx4 v134, s[22:23]
	s_add_i32 m0, s21, 0x2000
	s_nop 0
	global_load_lds_dwordx4 v130, s[22:23]
	s_waitcnt vmcnt(6)
	s_waitcnt lgkmcnt(0)
	s_barrier
	s_setprio 1
	v_mfma_f32_16x16x32_bf16 v[62:65], v[148:151], v[172:175], v[62:65]
	v_mfma_f32_16x16x32_bf16 v[58:61], v[156:159], v[172:175], v[58:61]
	v_mfma_f32_16x16x32_bf16 v[46:49], v[148:151], v[184:187], v[46:49]
	v_mfma_f32_16x16x32_bf16 v[42:45], v[156:159], v[184:187], v[42:45]
	v_mfma_f32_16x16x32_bf16 v[28:31], v[148:151], v[192:195], v[28:31]
	v_mfma_f32_16x16x32_bf16 v[24:27], v[156:159], v[192:195], v[24:27]
	v_mfma_f32_16x16x32_bf16 v[12:15], v[148:151], v[200:203], v[12:15]
	v_mfma_f32_16x16x32_bf16 v[8:11], v[156:159], v[200:203], v[8:11]
	v_mfma_f32_16x16x32_bf16 v[62:65], v[152:155], v[180:183], v[62:65]
	v_mfma_f32_16x16x32_bf16 v[58:61], v[160:163], v[180:183], v[58:61]
	v_mfma_f32_16x16x32_bf16 v[46:49], v[152:155], v[188:191], v[46:49]
	v_mfma_f32_16x16x32_bf16 v[42:45], v[160:163], v[188:191], v[42:45]
	v_mfma_f32_16x16x32_bf16 v[28:31], v[152:155], v[196:199], v[28:31]
	v_mfma_f32_16x16x32_bf16 v[24:27], v[160:163], v[196:199], v[24:27]
	v_mfma_f32_16x16x32_bf16 v[12:15], v[152:155], v[204:207], v[12:15]
	v_mfma_f32_16x16x32_bf16 v[8:11], v[160:163], v[204:207], v[8:11]
	v_mfma_f32_16x16x32_bf16 v[54:57], v[208:211], v[172:175], v[54:57]
	v_mfma_f32_16x16x32_bf16 v[50:53], v[216:219], v[172:175], v[50:53]
	v_mfma_f32_16x16x32_bf16 v[38:41], v[208:211], v[184:187], v[38:41]
	v_mfma_f32_16x16x32_bf16 v[34:37], v[216:219], v[184:187], v[34:37]
	v_mfma_f32_16x16x32_bf16 v[20:23], v[208:211], v[192:195], v[20:23]
	v_mfma_f32_16x16x32_bf16 v[16:19], v[216:219], v[192:195], v[16:19]
	v_mfma_f32_16x16x32_bf16 v[4:7], v[208:211], v[200:203], v[4:7]
	v_mfma_f32_16x16x32_bf16 v[0:3], v[216:219], v[200:203], v[0:3]
	v_mfma_f32_16x16x32_bf16 v[54:57], v[212:215], v[180:183], v[54:57]
	v_mfma_f32_16x16x32_bf16 v[50:53], v[220:223], v[180:183], v[50:53]
	v_mfma_f32_16x16x32_bf16 v[38:41], v[212:215], v[188:191], v[38:41]
	v_mfma_f32_16x16x32_bf16 v[34:37], v[220:223], v[188:191], v[34:37]
	v_mfma_f32_16x16x32_bf16 v[20:23], v[212:215], v[196:199], v[20:23]
	v_mfma_f32_16x16x32_bf16 v[16:19], v[220:223], v[196:199], v[16:19]
	v_mfma_f32_16x16x32_bf16 v[4:7], v[212:215], v[204:207], v[4:7]
	v_mfma_f32_16x16x32_bf16 v[0:3], v[220:223], v[204:207], v[0:3]
	s_setprio 0
	s_add_i32 s21, 0, 0x18000
	v_add_u32_e32 v143, s21, v167
	s_barrier
	ds_read_b128 v[148:151], v143
	ds_read_b128 v[152:155], v143 offset:1024
	ds_read_b128 v[156:159], v143 offset:2048
	ds_read_b128 v[160:163], v143 offset:3072
	s_add_u32 s10, s10, 0x80000
	s_addc_u32 s11, s11, 0
	s_add_i32 s22, 0, 0x1c000
	v_add_u32_e32 v143, s22, v167
	ds_read_b128 v[208:211], v143
	ds_read_b128 v[212:215], v143 offset:1024
	ds_read_b128 v[216:219], v143 offset:2048
	ds_read_b128 v[220:223], v143 offset:3072
	s_mov_b32 m0, s42
	s_nop 0
	global_load_lds_dwordx4 v136, s[10:11]
	ds_read_b128 v[172:175], v171 offset:32768
	ds_read_b128 v[180:183], v171 offset:33792
	ds_read_b128 v[184:187], v171 offset:34816
	ds_read_b128 v[188:191], v171 offset:35840
	ds_read_b128 v[192:195], v171 offset:36864
	ds_read_b128 v[196:199], v171 offset:37888
	ds_read_b128 v[200:203], v171 offset:38912
	ds_read_b128 v[204:207], v171 offset:39936
	s_mov_b32 m0, s43
	s_nop 0
	global_load_lds_dwordx4 v132, s[10:11]
	s_waitcnt lgkmcnt(0)
	s_barrier
	s_setprio 1
	v_mfma_f32_16x16x32_bf16 v[126:129], v[148:151], v[172:175], v[126:129]
	v_mfma_f32_16x16x32_bf16 v[122:125], v[156:159], v[172:175], v[122:125]
	v_mfma_f32_16x16x32_bf16 v[110:113], v[148:151], v[184:187], v[110:113]
	v_mfma_f32_16x16x32_bf16 v[106:109], v[156:159], v[184:187], v[106:109]
	v_mfma_f32_16x16x32_bf16 v[94:97], v[148:151], v[192:195], v[94:97]
	v_mfma_f32_16x16x32_bf16 v[90:93], v[156:159], v[192:195], v[90:93]
	v_mfma_f32_16x16x32_bf16 v[78:81], v[148:151], v[200:203], v[78:81]
	v_mfma_f32_16x16x32_bf16 v[74:77], v[156:159], v[200:203], v[74:77]
	v_mfma_f32_16x16x32_bf16 v[126:129], v[152:155], v[180:183], v[126:129]
	v_mfma_f32_16x16x32_bf16 v[122:125], v[160:163], v[180:183], v[122:125]
	v_mfma_f32_16x16x32_bf16 v[110:113], v[152:155], v[188:191], v[110:113]
	v_mfma_f32_16x16x32_bf16 v[106:109], v[160:163], v[188:191], v[106:109]
	v_mfma_f32_16x16x32_bf16 v[94:97], v[152:155], v[196:199], v[94:97]
	v_mfma_f32_16x16x32_bf16 v[90:93], v[160:163], v[196:199], v[90:93]
	v_mfma_f32_16x16x32_bf16 v[78:81], v[152:155], v[204:207], v[78:81]
	v_mfma_f32_16x16x32_bf16 v[74:77], v[160:163], v[204:207], v[74:77]
	v_mfma_f32_16x16x32_bf16 v[118:121], v[208:211], v[172:175], v[118:121]
	v_mfma_f32_16x16x32_bf16 v[114:117], v[216:219], v[172:175], v[114:117]
	v_mfma_f32_16x16x32_bf16 v[102:105], v[208:211], v[184:187], v[102:105]
	v_mfma_f32_16x16x32_bf16 v[98:101], v[216:219], v[184:187], v[98:101]
	v_mfma_f32_16x16x32_bf16 v[86:89], v[208:211], v[192:195], v[86:89]
	v_mfma_f32_16x16x32_bf16 v[82:85], v[216:219], v[192:195], v[82:85]
	v_mfma_f32_16x16x32_bf16 v[70:73], v[208:211], v[200:203], v[70:73]
	v_mfma_f32_16x16x32_bf16 v[66:69], v[216:219], v[200:203], v[66:69]
	v_mfma_f32_16x16x32_bf16 v[118:121], v[212:215], v[180:183], v[118:121]
	v_mfma_f32_16x16x32_bf16 v[114:117], v[220:223], v[180:183], v[114:117]
	v_mfma_f32_16x16x32_bf16 v[102:105], v[212:215], v[188:191], v[102:105]
	v_mfma_f32_16x16x32_bf16 v[98:101], v[220:223], v[188:191], v[98:101]
	v_mfma_f32_16x16x32_bf16 v[86:89], v[212:215], v[196:199], v[86:89]
	v_mfma_f32_16x16x32_bf16 v[82:85], v[220:223], v[196:199], v[82:85]
	v_mfma_f32_16x16x32_bf16 v[70:73], v[212:215], v[204:207], v[70:73]
	v_mfma_f32_16x16x32_bf16 v[66:69], v[220:223], v[204:207], v[66:69]
	s_setprio 0
	s_barrier
	ds_read_b128 v[172:175], v171 offset:49152
	ds_read_b128 v[180:183], v171 offset:50176
	ds_read_b128 v[184:187], v171 offset:51200
	ds_read_b128 v[188:191], v171 offset:52224
	ds_read_b128 v[192:195], v171 offset:53248
	ds_read_b128 v[196:199], v171 offset:54272
	ds_read_b128 v[200:203], v171 offset:55296
	ds_read_b128 v[204:207], v171 offset:56320
	s_add_i32 s11, s21, s39
	v_lshl_add_u64 v[164:165], v[164:165], 0, s[88:89]
	s_mov_b32 m0, s11
	s_nop 0
	global_load_lds_dwordx4 v[164:165], off
	v_lshl_add_u64 v[164:165], v[176:177], 0, s[88:89]
	s_add_i32 m0, s11, 0x2000
	s_nop 0
	global_load_lds_dwordx4 v[164:165], off
	s_mov_b32 m0, s46
	v_lshl_add_u64 v[164:165], v[224:225], 0, s[88:89]
	s_nop 0
	global_load_lds_dwordx4 v[164:165], off
	v_lshl_add_u64 v[164:165], v[236:237], 0, s[88:89]
	s_mov_b32 m0, s47
	s_nop 0
	global_load_lds_dwordx4 v[164:165], off
	s_add_u32 s8, s8, 0x80080
	s_addc_u32 s9, s9, 0
	s_add_i32 s10, s39, 0x1c000
	s_mov_b32 m0, s10
	s_nop 0
	global_load_lds_dwordx4 v134, s[8:9]
	s_add_i32 m0, s10, 0x2000
	s_nop 0
	global_load_lds_dwordx4 v130, s[8:9]
	s_waitcnt vmcnt(6)
	s_waitcnt lgkmcnt(0)
	s_barrier
	s_setprio 1
	v_mfma_f32_16x16x32_bf16 v[62:65], v[148:151], v[172:175], v[62:65]
	v_mfma_f32_16x16x32_bf16 v[58:61], v[156:159], v[172:175], v[58:61]
	v_mfma_f32_16x16x32_bf16 v[46:49], v[148:151], v[184:187], v[46:49]
	v_mfma_f32_16x16x32_bf16 v[42:45], v[156:159], v[184:187], v[42:45]
	v_mfma_f32_16x16x32_bf16 v[28:31], v[148:151], v[192:195], v[28:31]
	v_mfma_f32_16x16x32_bf16 v[24:27], v[156:159], v[192:195], v[24:27]
	v_mfma_f32_16x16x32_bf16 v[12:15], v[148:151], v[200:203], v[12:15]
	v_mfma_f32_16x16x32_bf16 v[8:11], v[156:159], v[200:203], v[8:11]
	v_mfma_f32_16x16x32_bf16 v[62:65], v[152:155], v[180:183], v[62:65]
	v_mfma_f32_16x16x32_bf16 v[58:61], v[160:163], v[180:183], v[58:61]
	v_mfma_f32_16x16x32_bf16 v[46:49], v[152:155], v[188:191], v[46:49]
	v_mfma_f32_16x16x32_bf16 v[42:45], v[160:163], v[188:191], v[42:45]
	v_mfma_f32_16x16x32_bf16 v[28:31], v[152:155], v[196:199], v[28:31]
	v_mfma_f32_16x16x32_bf16 v[24:27], v[160:163], v[196:199], v[24:27]
	v_mfma_f32_16x16x32_bf16 v[12:15], v[152:155], v[204:207], v[12:15]
	v_mfma_f32_16x16x32_bf16 v[8:11], v[160:163], v[204:207], v[8:11]
	v_mfma_f32_16x16x32_bf16 v[54:57], v[208:211], v[172:175], v[54:57]
	v_mfma_f32_16x16x32_bf16 v[50:53], v[216:219], v[172:175], v[50:53]
	v_mfma_f32_16x16x32_bf16 v[38:41], v[208:211], v[184:187], v[38:41]
	v_mfma_f32_16x16x32_bf16 v[34:37], v[216:219], v[184:187], v[34:37]
	v_mfma_f32_16x16x32_bf16 v[20:23], v[208:211], v[192:195], v[20:23]
	v_mfma_f32_16x16x32_bf16 v[16:19], v[216:219], v[192:195], v[16:19]
	v_mfma_f32_16x16x32_bf16 v[4:7], v[208:211], v[200:203], v[4:7]
	v_mfma_f32_16x16x32_bf16 v[0:3], v[216:219], v[200:203], v[0:3]
	v_mfma_f32_16x16x32_bf16 v[54:57], v[212:215], v[180:183], v[54:57]
	v_mfma_f32_16x16x32_bf16 v[50:53], v[220:223], v[180:183], v[50:53]
	v_mfma_f32_16x16x32_bf16 v[38:41], v[212:215], v[188:191], v[38:41]
	v_mfma_f32_16x16x32_bf16 v[34:37], v[220:223], v[188:191], v[34:37]
	v_mfma_f32_16x16x32_bf16 v[20:23], v[212:215], v[196:199], v[20:23]
	v_mfma_f32_16x16x32_bf16 v[16:19], v[220:223], v[196:199], v[16:19]
	v_mfma_f32_16x16x32_bf16 v[4:7], v[212:215], v[204:207], v[4:7]
	v_mfma_f32_16x16x32_bf16 v[0:3], v[220:223], v[204:207], v[0:3]
	s_setprio 0
	s_add_i32 s20, s20, 2
	s_add_u32 s6, s6, 0x100
	s_addc_u32 s7, s7, 0
	s_add_u32 s13, s13, 0x100
	s_addc_u32 s15, s15, 0
	s_cmp_gt_u32 s20, 29
	s_barrier
	s_cbranch_scc0 .LBB0_372
	s_sub_i32 s6, s51, 8
	s_cmp_lt_u32 s6, 8
	s_cbranch_scc1 .Lmain_old
	s_sub_i32 s6, s51, 32
	s_cmp_lt_u32 s6, 12
	s_cbranch_scc1 .Lmain_kv
	v_mbcnt_lo_u32_b32 v217, -1, 0
	v_mbcnt_hi_u32_b32 v217, -1, v217
	v_lshrrev_b32_e32 v208, 4, v217
	v_bfe_u32 v209, v217, 2, 2
	v_and_b32_e32 v210, 3, v217
	v_lshl_add_u32 v235, v208, 2, v209
	v_lshl_add_u32 v217, v210, 4, v235
	v_lshlrev_b32_e32 v217, 2, v217
	v_add_u32_e32 v235, s45, v235
	v_lshlrev_b32_e32 v210, 4, v210
	s_lshl_b32 s6, s44, 6
	v_add_u32_e32 v210, s6, v210
	s_cmp_ge_u32 s51, 0x44
	s_cbranch_scc1 .Lmain_sig
	s_sub_i32 s6, s51, 44
	s_mov_b32 s7, 0x25e51000
	s_mov_b32 s13, 0x15e51000
	s_cmp_lt_i32 s6, 0
	s_cselect_b32 s6, s51, s6
	s_cselect_b32 s7, s13, s7
	s_lshr_b32 s13, s6, 3
	s_lshl_b32 s13, s13, 26
	s_add_i32 s7, s7, s13
	s_and_b32 s6, s6, 7
	s_lshl_b32 s6, s6, 9
	s_add_i32 s7, s7, s6
	s_lshl_b32 s6, s31, 20
	s_add_i32 s7, s7, s6
	s_add_u32 s22, s76, s7
	s_addc_u32 s23, s77, 0
	v_lshl_add_u32 v235, v235, 12, v210
	s_lshr_b32 s6, s51, 3
	s_cmp_eq_u32 s6, 3
	s_cbranch_scc1 .Lmain_q
	s_add_u32 s10, s22, 0
	s_addc_u32 s11, s23, 0
	v_cvt_pk_bf16_f32 v148, v126, v127
	v_cvt_pk_bf16_f32 v149, v128, v129
	v_cvt_pk_bf16_f32 v150, v122, v123
	v_cvt_pk_bf16_f32 v151, v124, v125
	ds_bpermute_b32 v238, v217, v148
	ds_bpermute_b32 v239, v217, v149
	ds_bpermute_b32 v240, v217, v150
	ds_bpermute_b32 v241, v217, v151
	v_cvt_pk_bf16_f32 v152, v118, v119
	v_cvt_pk_bf16_f32 v153, v120, v121
	v_cvt_pk_bf16_f32 v154, v114, v115
	v_cvt_pk_bf16_f32 v155, v116, v117
	ds_bpermute_b32 v242, v217, v152
	ds_bpermute_b32 v243, v217, v153
	ds_bpermute_b32 v244, v217, v154
	ds_bpermute_b32 v245, v217, v155
	s_add_u32 s20, s22, 0x10000
	s_addc_u32 s21, s23, 0
	v_cvt_pk_bf16_f32 v156, v110, v111
	v_cvt_pk_bf16_f32 v157, v112, v113
	v_cvt_pk_bf16_f32 v158, v106, v107
	v_cvt_pk_bf16_f32 v159, v108, v109
	ds_bpermute_b32 v246, v217, v156
	ds_bpermute_b32 v247, v217, v157
	ds_bpermute_b32 v248, v217, v158
	ds_bpermute_b32 v249, v217, v159
	v_cvt_pk_bf16_f32 v160, v102, v103
	v_cvt_pk_bf16_f32 v161, v104, v105
	v_cvt_pk_bf16_f32 v162, v98, v99
	v_cvt_pk_bf16_f32 v163, v100, v101
	ds_bpermute_b32 v250, v217, v160
	ds_bpermute_b32 v251, v217, v161
	ds_bpermute_b32 v252, v217, v162
	ds_bpermute_b32 v253, v217, v163
	s_waitcnt lgkmcnt(0)
	global_store_dwordx4 v235, v[238:241], s[10:11] sc0 sc1
	global_store_dwordx4 v235, v[242:245], s[10:11] offset:256 sc0 sc1
	global_store_dwordx4 v235, v[246:249], s[20:21] sc0 sc1
	global_store_dwordx4 v235, v[250:253], s[20:21] offset:256 sc0 sc1
	s_add_u32 s10, s22, 0x20000
	s_addc_u32 s11, s23, 0
	v_cvt_pk_bf16_f32 v148, v94, v95
	v_cvt_pk_bf16_f32 v149, v96, v97
	v_cvt_pk_bf16_f32 v150, v90, v91
	v_cvt_pk_bf16_f32 v151, v92, v93
	ds_bpermute_b32 v238, v217, v148
	ds_bpermute_b32 v239, v217, v149
	ds_bpermute_b32 v240, v217, v150
	ds_bpermute_b32 v241, v217, v151
	v_cvt_pk_bf16_f32 v152, v86, v87
	v_cvt_pk_bf16_f32 v153, v88, v89
	v_cvt_pk_bf16_f32 v154, v82, v83
	v_cvt_pk_bf16_f32 v155, v84, v85
	ds_bpermute_b32 v242, v217, v152
	ds_bpermute_b32 v243, v217, v153
	ds_bpermute_b32 v244, v217, v154
	ds_bpermute_b32 v245, v217, v155
	s_add_u32 s20, s22, 0x30000
	s_addc_u32 s21, s23, 0
	v_cvt_pk_bf16_f32 v156, v78, v79
	v_cvt_pk_bf16_f32 v157, v80, v81
	v_cvt_pk_bf16_f32 v158, v74, v75
	v_cvt_pk_bf16_f32 v159, v76, v77
	ds_bpermute_b32 v246, v217, v156
	ds_bpermute_b32 v247, v217, v157
	ds_bpermute_b32 v248, v217, v158
	ds_bpermute_b32 v249, v217, v159
	v_cvt_pk_bf16_f32 v160, v70, v71
	v_cvt_pk_bf16_f32 v161, v72, v73
	v_cvt_pk_bf16_f32 v162, v66, v67
	v_cvt_pk_bf16_f32 v163, v68, v69
	ds_bpermute_b32 v250, v217, v160
	ds_bpermute_b32 v251, v217, v161
	ds_bpermute_b32 v252, v217, v162
	ds_bpermute_b32 v253, v217, v163
	s_waitcnt lgkmcnt(0)
	global_store_dwordx4 v235, v[238:241], s[10:11] sc0 sc1
	global_store_dwordx4 v235, v[242:245], s[10:11] offset:256 sc0 sc1
	global_store_dwordx4 v235, v[246:249], s[20:21] sc0 sc1
	global_store_dwordx4 v235, v[250:253], s[20:21] offset:256 sc0 sc1
	s_add_u32 s10, s22, 0x80000
	s_addc_u32 s11, s23, 0
	v_cvt_pk_bf16_f32 v148, v62, v63
	v_cvt_pk_bf16_f32 v149, v64, v65
	v_cvt_pk_bf16_f32 v150, v58, v59
	v_cvt_pk_bf16_f32 v151, v60, v61
	ds_bpermute_b32 v238, v217, v148
	ds_bpermute_b32 v239, v217, v149
	ds_bpermute_b32 v240, v217, v150
	ds_bpermute_b32 v241, v217, v151
	v_cvt_pk_bf16_f32 v152, v54, v55
	v_cvt_pk_bf16_f32 v153, v56, v57
	v_cvt_pk_bf16_f32 v154, v50, v51
	v_cvt_pk_bf16_f32 v155, v52, v53
	ds_bpermute_b32 v242, v217, v152
	ds_bpermute_b32 v243, v217, v153
	ds_bpermute_b32 v244, v217, v154
	ds_bpermute_b32 v245, v217, v155
	s_add_u32 s20, s22, 0x90000
	s_addc_u32 s21, s23, 0
	v_cvt_pk_bf16_f32 v156, v46, v47
	v_cvt_pk_bf16_f32 v157, v48, v49
	v_cvt_pk_bf16_f32 v158, v42, v43
	v_cvt_pk_bf16_f32 v159, v44, v45
	ds_bpermute_b32 v246, v217, v156
	ds_bpermute_b32 v247, v217, v157
	ds_bpermute_b32 v248, v217, v158
	ds_bpermute_b32 v249, v217, v159
	v_cvt_pk_bf16_f32 v160, v38, v39
	v_cvt_pk_bf16_f32 v161, v40, v41
	v_cvt_pk_bf16_f32 v162, v34, v35
	v_cvt_pk_bf16_f32 v163, v36, v37
	ds_bpermute_b32 v250, v217, v160
	ds_bpermute_b32 v251, v217, v161
	ds_bpermute_b32 v252, v217, v162
	ds_bpermute_b32 v253, v217, v163
	s_waitcnt lgkmcnt(0)
	global_store_dwordx4 v235, v[238:241], s[10:11] sc0 sc1
	global_store_dwordx4 v235, v[242:245], s[10:11] offset:256 sc0 sc1
	global_store_dwordx4 v235, v[246:249], s[20:21] sc0 sc1
	global_store_dwordx4 v235, v[250:253], s[20:21] offset:256 sc0 sc1
	s_add_u32 s10, s22, 0xa0000
	s_addc_u32 s11, s23, 0
	v_cvt_pk_bf16_f32 v148, v28, v29
	v_cvt_pk_bf16_f32 v149, v30, v31
	v_cvt_pk_bf16_f32 v150, v24, v25
	v_cvt_pk_bf16_f32 v151, v26, v27
	ds_bpermute_b32 v238, v217, v148
	ds_bpermute_b32 v239, v217, v149
	ds_bpermute_b32 v240, v217, v150
	ds_bpermute_b32 v241, v217, v151
	v_cvt_pk_bf16_f32 v152, v20, v21
	v_cvt_pk_bf16_f32 v153, v22, v23
	v_cvt_pk_bf16_f32 v154, v16, v17
	v_cvt_pk_bf16_f32 v155, v18, v19
	ds_bpermute_b32 v242, v217, v152
	ds_bpermute_b32 v243, v217, v153
	ds_bpermute_b32 v244, v217, v154
	ds_bpermute_b32 v245, v217, v155
	s_add_u32 s20, s22, 0xb0000
	s_addc_u32 s21, s23, 0
	v_cvt_pk_bf16_f32 v156, v12, v13
	v_cvt_pk_bf16_f32 v157, v14, v15
	v_cvt_pk_bf16_f32 v158, v8, v9
	v_cvt_pk_bf16_f32 v159, v10, v11
	ds_bpermute_b32 v246, v217, v156
	ds_bpermute_b32 v247, v217, v157
	ds_bpermute_b32 v248, v217, v158
	ds_bpermute_b32 v249, v217, v159
	v_cvt_pk_bf16_f32 v160, v4, v5
	v_cvt_pk_bf16_f32 v161, v6, v7
	v_cvt_pk_bf16_f32 v162, v0, v1
	v_cvt_pk_bf16_f32 v163, v2, v3
	ds_bpermute_b32 v250, v217, v160
	ds_bpermute_b32 v251, v217, v161
	ds_bpermute_b32 v252, v217, v162
	ds_bpermute_b32 v253, v217, v163
	s_waitcnt lgkmcnt(0)
	global_store_dwordx4 v235, v[238:241], s[10:11] sc0 sc1
	global_store_dwordx4 v235, v[242:245], s[10:11] offset:256 sc0 sc1
	global_store_dwordx4 v235, v[246:249], s[20:21] sc0 sc1
	global_store_dwordx4 v235, v[250:253], s[20:21] offset:256 sc0 sc1
	s_branch .Lmain_latch_fast
.Lmain_q:
	s_mov_b32 s6, 0x3e0293ee
	s_add_u32 s10, s22, 0
	s_addc_u32 s11, s23, 0
	v_pk_mul_f32 v[126:127], v[126:127], s[6:7] op_sel_hi:[1,0]
	v_pk_mul_f32 v[128:129], v[128:129], s[6:7] op_sel_hi:[1,0]
	v_pk_mul_f32 v[122:123], v[122:123], s[6:7] op_sel_hi:[1,0]
	v_pk_mul_f32 v[124:125], v[124:125], s[6:7] op_sel_hi:[1,0]
	v_cvt_pk_bf16_f32 v148, v126, v127
	v_cvt_pk_bf16_f32 v149, v128, v129
	v_cvt_pk_bf16_f32 v150, v122, v123
	v_cvt_pk_bf16_f32 v151, v124, v125
	ds_bpermute_b32 v238, v217, v148
	ds_bpermute_b32 v239, v217, v149
	ds_bpermute_b32 v240, v217, v150
	ds_bpermute_b32 v241, v217, v151
	v_pk_mul_f32 v[118:119], v[118:119], s[6:7] op_sel_hi:[1,0]
	v_pk_mul_f32 v[120:121], v[120:121], s[6:7] op_sel_hi:[1,0]
	v_pk_mul_f32 v[114:115], v[114:115], s[6:7] op_sel_hi:[1,0]
	v_pk_mul_f32 v[116:117], v[116:117], s[6:7] op_sel_hi:[1,0]
	v_cvt_pk_bf16_f32 v152, v118, v119
	v_cvt_pk_bf16_f32 v153, v120, v121
	v_cvt_pk_bf16_f32 v154, v114, v115
	v_cvt_pk_bf16_f32 v155, v116, v117
	ds_bpermute_b32 v242, v217, v152
	ds_bpermute_b32 v243, v217, v153
	ds_bpermute_b32 v244, v217, v154
	ds_bpermute_b32 v245, v217, v155
	s_add_u32 s20, s22, 0x10000
	s_addc_u32 s21, s23, 0
	v_pk_mul_f32 v[110:111], v[110:111], s[6:7] op_sel_hi:[1,0]
	v_pk_mul_f32 v[112:113], v[112:113], s[6:7] op_sel_hi:[1,0]
	v_pk_mul_f32 v[106:107], v[106:107], s[6:7] op_sel_hi:[1,0]
	v_pk_mul_f32 v[108:109], v[108:109], s[6:7] op_sel_hi:[1,0]
	v_cvt_pk_bf16_f32 v156, v110, v111
	v_cvt_pk_bf16_f32 v157, v112, v113
	v_cvt_pk_bf16_f32 v158, v106, v107
	v_cvt_pk_bf16_f32 v159, v108, v109
	ds_bpermute_b32 v246, v217, v156
	ds_bpermute_b32 v247, v217, v157
	ds_bpermute_b32 v248, v217, v158
	ds_bpermute_b32 v249, v217, v159
	v_pk_mul_f32 v[102:103], v[102:103], s[6:7] op_sel_hi:[1,0]
	v_pk_mul_f32 v[104:105], v[104:105], s[6:7] op_sel_hi:[1,0]
	v_pk_mul_f32 v[98:99], v[98:99], s[6:7] op_sel_hi:[1,0]
	v_pk_mul_f32 v[100:101], v[100:101], s[6:7] op_sel_hi:[1,0]
	v_cvt_pk_bf16_f32 v160, v102, v103
	v_cvt_pk_bf16_f32 v161, v104, v105
	v_cvt_pk_bf16_f32 v162, v98, v99
	v_cvt_pk_bf16_f32 v163, v100, v101
	ds_bpermute_b32 v250, v217, v160
	ds_bpermute_b32 v251, v217, v161
	ds_bpermute_b32 v252, v217, v162
	ds_bpermute_b32 v253, v217, v163
	s_waitcnt lgkmcnt(0)
	global_store_dwordx4 v235, v[238:241], s[10:11] sc0 sc1
	global_store_dwordx4 v235, v[242:245], s[10:11] offset:256 sc0 sc1
	global_store_dwordx4 v235, v[246:249], s[20:21] sc0 sc1
	global_store_dwordx4 v235, v[250:253], s[20:21] offset:256 sc0 sc1
	s_add_u32 s10, s22, 0x20000
	s_addc_u32 s11, s23, 0
	v_pk_mul_f32 v[94:95], v[94:95], s[6:7] op_sel_hi:[1,0]
	v_pk_mul_f32 v[96:97], v[96:97], s[6:7] op_sel_hi:[1,0]
	v_pk_mul_f32 v[90:91], v[90:91], s[6:7] op_sel_hi:[1,0]
	v_pk_mul_f32 v[92:93], v[92:93], s[6:7] op_sel_hi:[1,0]
	v_cvt_pk_bf16_f32 v148, v94, v95
	v_cvt_pk_bf16_f32 v149, v96, v97
	v_cvt_pk_bf16_f32 v150, v90, v91
	v_cvt_pk_bf16_f32 v151, v92, v93
	ds_bpermute_b32 v238, v217, v148
	ds_bpermute_b32 v239, v217, v149
	ds_bpermute_b32 v240, v217, v150
	ds_bpermute_b32 v241, v217, v151
	v_pk_mul_f32 v[86:87], v[86:87], s[6:7] op_sel_hi:[1,0]
	v_pk_mul_f32 v[88:89], v[88:89], s[6:7] op_sel_hi:[1,0]
	v_pk_mul_f32 v[82:83], v[82:83], s[6:7] op_sel_hi:[1,0]
	v_pk_mul_f32 v[84:85], v[84:85], s[6:7] op_sel_hi:[1,0]
	v_cvt_pk_bf16_f32 v152, v86, v87
	v_cvt_pk_bf16_f32 v153, v88, v89
	v_cvt_pk_bf16_f32 v154, v82, v83
	v_cvt_pk_bf16_f32 v155, v84, v85
	ds_bpermute_b32 v242, v217, v152
	ds_bpermute_b32 v243, v217, v153
	ds_bpermute_b32 v244, v217, v154
	ds_bpermute_b32 v245, v217, v155
	s_add_u32 s20, s22, 0x30000
	s_addc_u32 s21, s23, 0
	v_pk_mul_f32 v[78:79], v[78:79], s[6:7] op_sel_hi:[1,0]
	v_pk_mul_f32 v[80:81], v[80:81], s[6:7] op_sel_hi:[1,0]
	v_pk_mul_f32 v[74:75], v[74:75], s[6:7] op_sel_hi:[1,0]
	v_pk_mul_f32 v[76:77], v[76:77], s[6:7] op_sel_hi:[1,0]
	v_cvt_pk_bf16_f32 v156, v78, v79
	v_cvt_pk_bf16_f32 v157, v80, v81
	v_cvt_pk_bf16_f32 v158, v74, v75
	v_cvt_pk_bf16_f32 v159, v76, v77
	ds_bpermute_b32 v246, v217, v156
	ds_bpermute_b32 v247, v217, v157
	ds_bpermute_b32 v248, v217, v158
	ds_bpermute_b32 v249, v217, v159
	v_pk_mul_f32 v[70:71], v[70:71], s[6:7] op_sel_hi:[1,0]
	v_pk_mul_f32 v[72:73], v[72:73], s[6:7] op_sel_hi:[1,0]
	v_pk_mul_f32 v[66:67], v[66:67], s[6:7] op_sel_hi:[1,0]
	v_pk_mul_f32 v[68:69], v[68:69], s[6:7] op_sel_hi:[1,0]
	v_cvt_pk_bf16_f32 v160, v70, v71
	v_cvt_pk_bf16_f32 v161, v72, v73
	v_cvt_pk_bf16_f32 v162, v66, v67
	v_cvt_pk_bf16_f32 v163, v68, v69
	ds_bpermute_b32 v250, v217, v160
	ds_bpermute_b32 v251, v217, v161
	ds_bpermute_b32 v252, v217, v162
	ds_bpermute_b32 v253, v217, v163
	s_waitcnt lgkmcnt(0)
	global_store_dwordx4 v235, v[238:241], s[10:11] sc0 sc1
	global_store_dwordx4 v235, v[242:245], s[10:11] offset:256 sc0 sc1
	global_store_dwordx4 v235, v[246:249], s[20:21] sc0 sc1
	global_store_dwordx4 v235, v[250:253], s[20:21] offset:256 sc0 sc1
	s_add_u32 s10, s22, 0x80000
	s_addc_u32 s11, s23, 0
	v_pk_mul_f32 v[62:63], v[62:63], s[6:7] op_sel_hi:[1,0]
	v_pk_mul_f32 v[64:65], v[64:65], s[6:7] op_sel_hi:[1,0]
	v_pk_mul_f32 v[58:59], v[58:59], s[6:7] op_sel_hi:[1,0]
	v_pk_mul_f32 v[60:61], v[60:61], s[6:7] op_sel_hi:[1,0]
	v_cvt_pk_bf16_f32 v148, v62, v63
	v_cvt_pk_bf16_f32 v149, v64, v65
	v_cvt_pk_bf16_f32 v150, v58, v59
	v_cvt_pk_bf16_f32 v151, v60, v61
	ds_bpermute_b32 v238, v217, v148
	ds_bpermute_b32 v239, v217, v149
	ds_bpermute_b32 v240, v217, v150
	ds_bpermute_b32 v241, v217, v151
	v_pk_mul_f32 v[54:55], v[54:55], s[6:7] op_sel_hi:[1,0]
	v_pk_mul_f32 v[56:57], v[56:57], s[6:7] op_sel_hi:[1,0]
	v_pk_mul_f32 v[50:51], v[50:51], s[6:7] op_sel_hi:[1,0]
	v_pk_mul_f32 v[52:53], v[52:53], s[6:7] op_sel_hi:[1,0]
	v_cvt_pk_bf16_f32 v152, v54, v55
	v_cvt_pk_bf16_f32 v153, v56, v57
	v_cvt_pk_bf16_f32 v154, v50, v51
	v_cvt_pk_bf16_f32 v155, v52, v53
	ds_bpermute_b32 v242, v217, v152
	ds_bpermute_b32 v243, v217, v153
	ds_bpermute_b32 v244, v217, v154
	ds_bpermute_b32 v245, v217, v155
	s_add_u32 s20, s22, 0x90000
	s_addc_u32 s21, s23, 0
	v_pk_mul_f32 v[46:47], v[46:47], s[6:7] op_sel_hi:[1,0]
	v_pk_mul_f32 v[48:49], v[48:49], s[6:7] op_sel_hi:[1,0]
	v_pk_mul_f32 v[42:43], v[42:43], s[6:7] op_sel_hi:[1,0]
	v_pk_mul_f32 v[44:45], v[44:45], s[6:7] op_sel_hi:[1,0]
	v_cvt_pk_bf16_f32 v156, v46, v47
	v_cvt_pk_bf16_f32 v157, v48, v49
	v_cvt_pk_bf16_f32 v158, v42, v43
	v_cvt_pk_bf16_f32 v159, v44, v45
	ds_bpermute_b32 v246, v217, v156
	ds_bpermute_b32 v247, v217, v157
	ds_bpermute_b32 v248, v217, v158
	ds_bpermute_b32 v249, v217, v159
	v_pk_mul_f32 v[38:39], v[38:39], s[6:7] op_sel_hi:[1,0]
	v_pk_mul_f32 v[40:41], v[40:41], s[6:7] op_sel_hi:[1,0]
	v_pk_mul_f32 v[34:35], v[34:35], s[6:7] op_sel_hi:[1,0]
	v_pk_mul_f32 v[36:37], v[36:37], s[6:7] op_sel_hi:[1,0]
	v_cvt_pk_bf16_f32 v160, v38, v39
	v_cvt_pk_bf16_f32 v161, v40, v41
	v_cvt_pk_bf16_f32 v162, v34, v35
	v_cvt_pk_bf16_f32 v163, v36, v37
	ds_bpermute_b32 v250, v217, v160
	ds_bpermute_b32 v251, v217, v161
	ds_bpermute_b32 v252, v217, v162
	ds_bpermute_b32 v253, v217, v163
	s_waitcnt lgkmcnt(0)
	global_store_dwordx4 v235, v[238:241], s[10:11] sc0 sc1
	global_store_dwordx4 v235, v[242:245], s[10:11] offset:256 sc0 sc1
	global_store_dwordx4 v235, v[246:249], s[20:21] sc0 sc1
	global_store_dwordx4 v235, v[250:253], s[20:21] offset:256 sc0 sc1
	s_add_u32 s10, s22, 0xa0000
	s_addc_u32 s11, s23, 0
	v_pk_mul_f32 v[28:29], v[28:29], s[6:7] op_sel_hi:[1,0]
	v_pk_mul_f32 v[30:31], v[30:31], s[6:7] op_sel_hi:[1,0]
	v_pk_mul_f32 v[24:25], v[24:25], s[6:7] op_sel_hi:[1,0]
	v_pk_mul_f32 v[26:27], v[26:27], s[6:7] op_sel_hi:[1,0]
	v_cvt_pk_bf16_f32 v148, v28, v29
	v_cvt_pk_bf16_f32 v149, v30, v31
	v_cvt_pk_bf16_f32 v150, v24, v25
	v_cvt_pk_bf16_f32 v151, v26, v27
	ds_bpermute_b32 v238, v217, v148
	ds_bpermute_b32 v239, v217, v149
	ds_bpermute_b32 v240, v217, v150
	ds_bpermute_b32 v241, v217, v151
	v_pk_mul_f32 v[20:21], v[20:21], s[6:7] op_sel_hi:[1,0]
	v_pk_mul_f32 v[22:23], v[22:23], s[6:7] op_sel_hi:[1,0]
	v_pk_mul_f32 v[16:17], v[16:17], s[6:7] op_sel_hi:[1,0]
	v_pk_mul_f32 v[18:19], v[18:19], s[6:7] op_sel_hi:[1,0]
	v_cvt_pk_bf16_f32 v152, v20, v21
	v_cvt_pk_bf16_f32 v153, v22, v23
	v_cvt_pk_bf16_f32 v154, v16, v17
	v_cvt_pk_bf16_f32 v155, v18, v19
	ds_bpermute_b32 v242, v217, v152
	ds_bpermute_b32 v243, v217, v153
	ds_bpermute_b32 v244, v217, v154
	ds_bpermute_b32 v245, v217, v155
	s_add_u32 s20, s22, 0xb0000
	s_addc_u32 s21, s23, 0
	v_pk_mul_f32 v[12:13], v[12:13], s[6:7] op_sel_hi:[1,0]
	v_pk_mul_f32 v[14:15], v[14:15], s[6:7] op_sel_hi:[1,0]
	v_pk_mul_f32 v[8:9], v[8:9], s[6:7] op_sel_hi:[1,0]
	v_pk_mul_f32 v[10:11], v[10:11], s[6:7] op_sel_hi:[1,0]
	v_cvt_pk_bf16_f32 v156, v12, v13
	v_cvt_pk_bf16_f32 v157, v14, v15
	v_cvt_pk_bf16_f32 v158, v8, v9
	v_cvt_pk_bf16_f32 v159, v10, v11
	ds_bpermute_b32 v246, v217, v156
	ds_bpermute_b32 v247, v217, v157
	ds_bpermute_b32 v248, v217, v158
	ds_bpermute_b32 v249, v217, v159
	v_pk_mul_f32 v[4:5], v[4:5], s[6:7] op_sel_hi:[1,0]
	v_pk_mul_f32 v[6:7], v[6:7], s[6:7] op_sel_hi:[1,0]
	v_pk_mul_f32 v[0:1], v[0:1], s[6:7] op_sel_hi:[1,0]
	v_pk_mul_f32 v[2:3], v[2:3], s[6:7] op_sel_hi:[1,0]
	v_cvt_pk_bf16_f32 v160, v4, v5
	v_cvt_pk_bf16_f32 v161, v6, v7
	v_cvt_pk_bf16_f32 v162, v0, v1
	v_cvt_pk_bf16_f32 v163, v2, v3
	ds_bpermute_b32 v250, v217, v160
	ds_bpermute_b32 v251, v217, v161
	ds_bpermute_b32 v252, v217, v162
	ds_bpermute_b32 v253, v217, v163
	s_waitcnt lgkmcnt(0)
	global_store_dwordx4 v235, v[238:241], s[10:11] sc0 sc1
	global_store_dwordx4 v235, v[242:245], s[10:11] offset:256 sc0 sc1
	global_store_dwordx4 v235, v[246:249], s[20:21] sc0 sc1
	global_store_dwordx4 v235, v[250:253], s[20:21] offset:256 sc0 sc1
	s_branch .Lmain_latch_fast
.Lmain_sig:
	s_mul_i32 s7, s31, 0x300000
	s_sub_i32 s6, s51, 0x44
	s_lshl_b32 s6, s6, 9
	s_add_i32 s7, s7, s6
	s_add_i32 s7, s7, 0x37f51000
	s_add_u32 s22, s76, s7
	s_addc_u32 s23, s77, 0
	v_mul_u32_u24_e32 v235, 0x3000, v235
	v_add_u32_e32 v235, v235, v210
	s_add_u32 s10, s22, 0
	s_addc_u32 s11, s23, 0
	v_mul_f32_e32 v208, 0xbfb8aa3b, v126
	v_mul_f32_e32 v209, 0xbfb8aa3b, v127
	v_mul_f32_e32 v210, 0xbfb8aa3b, v128
	v_mul_f32_e32 v211, 0xbfb8aa3b, v129
	v_mul_f32_e32 v212, 0xbfb8aa3b, v122
	v_mul_f32_e32 v213, 0xbfb8aa3b, v123
	v_mul_f32_e32 v214, 0xbfb8aa3b, v124
	v_mul_f32_e32 v215, 0xbfb8aa3b, v125
	v_exp_f32_e32 v208, v208
	v_exp_f32_e32 v209, v209
	v_exp_f32_e32 v210, v210
	v_exp_f32_e32 v211, v211
	v_exp_f32_e32 v212, v212
	v_exp_f32_e32 v213, v213
	v_exp_f32_e32 v214, v214
	v_exp_f32_e32 v215, v215
	v_add_f32_e32 v208, 1.0, v208
	v_add_f32_e32 v209, 1.0, v209
	v_add_f32_e32 v210, 1.0, v210
	v_add_f32_e32 v211, 1.0, v211
	v_add_f32_e32 v212, 1.0, v212
	v_add_f32_e32 v213, 1.0, v213
	v_add_f32_e32 v214, 1.0, v214
	v_add_f32_e32 v215, 1.0, v215
	v_rcp_f32_e32 v208, v208
	v_rcp_f32_e32 v209, v209
	v_rcp_f32_e32 v210, v210
	v_rcp_f32_e32 v211, v211
	v_rcp_f32_e32 v212, v212
	v_rcp_f32_e32 v213, v213
	v_rcp_f32_e32 v214, v214
	v_rcp_f32_e32 v215, v215
	v_cvt_pk_bf16_f32 v148, v208, v209
	v_cvt_pk_bf16_f32 v149, v210, v211
	v_cvt_pk_bf16_f32 v150, v212, v213
	v_cvt_pk_bf16_f32 v151, v214, v215
	ds_bpermute_b32 v238, v217, v148
	ds_bpermute_b32 v239, v217, v149
	ds_bpermute_b32 v240, v217, v150
	ds_bpermute_b32 v241, v217, v151
	v_mul_f32_e32 v208, 0xbfb8aa3b, v118
	v_mul_f32_e32 v209, 0xbfb8aa3b, v119
	v_mul_f32_e32 v210, 0xbfb8aa3b, v120
	v_mul_f32_e32 v211, 0xbfb8aa3b, v121
	v_mul_f32_e32 v212, 0xbfb8aa3b, v114
	v_mul_f32_e32 v213, 0xbfb8aa3b, v115
	v_mul_f32_e32 v214, 0xbfb8aa3b, v116
	v_mul_f32_e32 v215, 0xbfb8aa3b, v117
	v_exp_f32_e32 v208, v208
	v_exp_f32_e32 v209, v209
	v_exp_f32_e32 v210, v210
	v_exp_f32_e32 v211, v211
	v_exp_f32_e32 v212, v212
	v_exp_f32_e32 v213, v213
	v_exp_f32_e32 v214, v214
	v_exp_f32_e32 v215, v215
	v_add_f32_e32 v208, 1.0, v208
	v_add_f32_e32 v209, 1.0, v209
	v_add_f32_e32 v210, 1.0, v210
	v_add_f32_e32 v211, 1.0, v211
	v_add_f32_e32 v212, 1.0, v212
	v_add_f32_e32 v213, 1.0, v213
	v_add_f32_e32 v214, 1.0, v214
	v_add_f32_e32 v215, 1.0, v215
	v_rcp_f32_e32 v208, v208
	v_rcp_f32_e32 v209, v209
	v_rcp_f32_e32 v210, v210
	v_rcp_f32_e32 v211, v211
	v_rcp_f32_e32 v212, v212
	v_rcp_f32_e32 v213, v213
	v_rcp_f32_e32 v214, v214
	v_rcp_f32_e32 v215, v215
	v_cvt_pk_bf16_f32 v152, v208, v209
	v_cvt_pk_bf16_f32 v153, v210, v211
	v_cvt_pk_bf16_f32 v154, v212, v213
	v_cvt_pk_bf16_f32 v155, v214, v215
	ds_bpermute_b32 v242, v217, v152
	ds_bpermute_b32 v243, v217, v153
	ds_bpermute_b32 v244, v217, v154
	ds_bpermute_b32 v245, v217, v155
	s_add_u32 s20, s22, 0x30000
	s_addc_u32 s21, s23, 0
	v_mul_f32_e32 v208, 0xbfb8aa3b, v110
	v_mul_f32_e32 v209, 0xbfb8aa3b, v111
	v_mul_f32_e32 v210, 0xbfb8aa3b, v112
	v_mul_f32_e32 v211, 0xbfb8aa3b, v113
	v_mul_f32_e32 v212, 0xbfb8aa3b, v106
	v_mul_f32_e32 v213, 0xbfb8aa3b, v107
	v_mul_f32_e32 v214, 0xbfb8aa3b, v108
	v_mul_f32_e32 v215, 0xbfb8aa3b, v109
	v_exp_f32_e32 v208, v208
	v_exp_f32_e32 v209, v209
	v_exp_f32_e32 v210, v210
	v_exp_f32_e32 v211, v211
	v_exp_f32_e32 v212, v212
	v_exp_f32_e32 v213, v213
	v_exp_f32_e32 v214, v214
	v_exp_f32_e32 v215, v215
	v_add_f32_e32 v208, 1.0, v208
	v_add_f32_e32 v209, 1.0, v209
	v_add_f32_e32 v210, 1.0, v210
	v_add_f32_e32 v211, 1.0, v211
	v_add_f32_e32 v212, 1.0, v212
	v_add_f32_e32 v213, 1.0, v213
	v_add_f32_e32 v214, 1.0, v214
	v_add_f32_e32 v215, 1.0, v215
	v_rcp_f32_e32 v208, v208
	v_rcp_f32_e32 v209, v209
	v_rcp_f32_e32 v210, v210
	v_rcp_f32_e32 v211, v211
	v_rcp_f32_e32 v212, v212
	v_rcp_f32_e32 v213, v213
	v_rcp_f32_e32 v214, v214
	v_rcp_f32_e32 v215, v215
	v_cvt_pk_bf16_f32 v156, v208, v209
	v_cvt_pk_bf16_f32 v157, v210, v211
	v_cvt_pk_bf16_f32 v158, v212, v213
	v_cvt_pk_bf16_f32 v159, v214, v215
	ds_bpermute_b32 v246, v217, v156
	ds_bpermute_b32 v247, v217, v157
	ds_bpermute_b32 v248, v217, v158
	ds_bpermute_b32 v249, v217, v159
	v_mul_f32_e32 v208, 0xbfb8aa3b, v102
	v_mul_f32_e32 v209, 0xbfb8aa3b, v103
	v_mul_f32_e32 v210, 0xbfb8aa3b, v104
	v_mul_f32_e32 v211, 0xbfb8aa3b, v105
	v_mul_f32_e32 v212, 0xbfb8aa3b, v98
	v_mul_f32_e32 v213, 0xbfb8aa3b, v99
	v_mul_f32_e32 v214, 0xbfb8aa3b, v100
	v_mul_f32_e32 v215, 0xbfb8aa3b, v101
	v_exp_f32_e32 v208, v208
	v_exp_f32_e32 v209, v209
	v_exp_f32_e32 v210, v210
	v_exp_f32_e32 v211, v211
	v_exp_f32_e32 v212, v212
	v_exp_f32_e32 v213, v213
	v_exp_f32_e32 v214, v214
	v_exp_f32_e32 v215, v215
	v_add_f32_e32 v208, 1.0, v208
	v_add_f32_e32 v209, 1.0, v209
	v_add_f32_e32 v210, 1.0, v210
	v_add_f32_e32 v211, 1.0, v211
	v_add_f32_e32 v212, 1.0, v212
	v_add_f32_e32 v213, 1.0, v213
	v_add_f32_e32 v214, 1.0, v214
	v_add_f32_e32 v215, 1.0, v215
	v_rcp_f32_e32 v208, v208
	v_rcp_f32_e32 v209, v209
	v_rcp_f32_e32 v210, v210
	v_rcp_f32_e32 v211, v211
	v_rcp_f32_e32 v212, v212
	v_rcp_f32_e32 v213, v213
	v_rcp_f32_e32 v214, v214
	v_rcp_f32_e32 v215, v215
	v_cvt_pk_bf16_f32 v160, v208, v209
	v_cvt_pk_bf16_f32 v161, v210, v211
	v_cvt_pk_bf16_f32 v162, v212, v213
	v_cvt_pk_bf16_f32 v163, v214, v215
	ds_bpermute_b32 v250, v217, v160
	ds_bpermute_b32 v251, v217, v161
	ds_bpermute_b32 v252, v217, v162
	ds_bpermute_b32 v253, v217, v163
	s_waitcnt lgkmcnt(0)
	global_store_dwordx4 v235, v[238:241], s[10:11] sc0 sc1
	global_store_dwordx4 v235, v[242:245], s[10:11] offset:256 sc0 sc1
	global_store_dwordx4 v235, v[246:249], s[20:21] sc0 sc1
	global_store_dwordx4 v235, v[250:253], s[20:21] offset:256 sc0 sc1
	s_add_u32 s10, s22, 0x60000
	s_addc_u32 s11, s23, 0
	v_mul_f32_e32 v208, 0xbfb8aa3b, v94
	v_mul_f32_e32 v209, 0xbfb8aa3b, v95
	v_mul_f32_e32 v210, 0xbfb8aa3b, v96
	v_mul_f32_e32 v211, 0xbfb8aa3b, v97
	v_mul_f32_e32 v212, 0xbfb8aa3b, v90
	v_mul_f32_e32 v213, 0xbfb8aa3b, v91
	v_mul_f32_e32 v214, 0xbfb8aa3b, v92
	v_mul_f32_e32 v215, 0xbfb8aa3b, v93
	v_exp_f32_e32 v208, v208
	v_exp_f32_e32 v209, v209
	v_exp_f32_e32 v210, v210
	v_exp_f32_e32 v211, v211
	v_exp_f32_e32 v212, v212
	v_exp_f32_e32 v213, v213
	v_exp_f32_e32 v214, v214
	v_exp_f32_e32 v215, v215
	v_add_f32_e32 v208, 1.0, v208
	v_add_f32_e32 v209, 1.0, v209
	v_add_f32_e32 v210, 1.0, v210
	v_add_f32_e32 v211, 1.0, v211
	v_add_f32_e32 v212, 1.0, v212
	v_add_f32_e32 v213, 1.0, v213
	v_add_f32_e32 v214, 1.0, v214
	v_add_f32_e32 v215, 1.0, v215
	v_rcp_f32_e32 v208, v208
	v_rcp_f32_e32 v209, v209
	v_rcp_f32_e32 v210, v210
	v_rcp_f32_e32 v211, v211
	v_rcp_f32_e32 v212, v212
	v_rcp_f32_e32 v213, v213
	v_rcp_f32_e32 v214, v214
	v_rcp_f32_e32 v215, v215
	v_cvt_pk_bf16_f32 v148, v208, v209
	v_cvt_pk_bf16_f32 v149, v210, v211
	v_cvt_pk_bf16_f32 v150, v212, v213
	v_cvt_pk_bf16_f32 v151, v214, v215
	ds_bpermute_b32 v238, v217, v148
	ds_bpermute_b32 v239, v217, v149
	ds_bpermute_b32 v240, v217, v150
	ds_bpermute_b32 v241, v217, v151
	v_mul_f32_e32 v208, 0xbfb8aa3b, v86
	v_mul_f32_e32 v209, 0xbfb8aa3b, v87
	v_mul_f32_e32 v210, 0xbfb8aa3b, v88
	v_mul_f32_e32 v211, 0xbfb8aa3b, v89
	v_mul_f32_e32 v212, 0xbfb8aa3b, v82
	v_mul_f32_e32 v213, 0xbfb8aa3b, v83
	v_mul_f32_e32 v214, 0xbfb8aa3b, v84
	v_mul_f32_e32 v215, 0xbfb8aa3b, v85
	v_exp_f32_e32 v208, v208
	v_exp_f32_e32 v209, v209
	v_exp_f32_e32 v210, v210
	v_exp_f32_e32 v211, v211
	v_exp_f32_e32 v212, v212
	v_exp_f32_e32 v213, v213
	v_exp_f32_e32 v214, v214
	v_exp_f32_e32 v215, v215
	v_add_f32_e32 v208, 1.0, v208
	v_add_f32_e32 v209, 1.0, v209
	v_add_f32_e32 v210, 1.0, v210
	v_add_f32_e32 v211, 1.0, v211
	v_add_f32_e32 v212, 1.0, v212
	v_add_f32_e32 v213, 1.0, v213
	v_add_f32_e32 v214, 1.0, v214
	v_add_f32_e32 v215, 1.0, v215
	v_rcp_f32_e32 v208, v208
	v_rcp_f32_e32 v209, v209
	v_rcp_f32_e32 v210, v210
	v_rcp_f32_e32 v211, v211
	v_rcp_f32_e32 v212, v212
	v_rcp_f32_e32 v213, v213
	v_rcp_f32_e32 v214, v214
	v_rcp_f32_e32 v215, v215
	v_cvt_pk_bf16_f32 v152, v208, v209
	v_cvt_pk_bf16_f32 v153, v210, v211
	v_cvt_pk_bf16_f32 v154, v212, v213
	v_cvt_pk_bf16_f32 v155, v214, v215
	ds_bpermute_b32 v242, v217, v152
	ds_bpermute_b32 v243, v217, v153
	ds_bpermute_b32 v244, v217, v154
	ds_bpermute_b32 v245, v217, v155
	s_add_u32 s20, s22, 0x90000
	s_addc_u32 s21, s23, 0
	v_mul_f32_e32 v208, 0xbfb8aa3b, v78
	v_mul_f32_e32 v209, 0xbfb8aa3b, v79
	v_mul_f32_e32 v210, 0xbfb8aa3b, v80
	v_mul_f32_e32 v211, 0xbfb8aa3b, v81
	v_mul_f32_e32 v212, 0xbfb8aa3b, v74
	v_mul_f32_e32 v213, 0xbfb8aa3b, v75
	v_mul_f32_e32 v214, 0xbfb8aa3b, v76
	v_mul_f32_e32 v215, 0xbfb8aa3b, v77
	v_exp_f32_e32 v208, v208
	v_exp_f32_e32 v209, v209
	v_exp_f32_e32 v210, v210
	v_exp_f32_e32 v211, v211
	v_exp_f32_e32 v212, v212
	v_exp_f32_e32 v213, v213
	v_exp_f32_e32 v214, v214
	v_exp_f32_e32 v215, v215
	v_add_f32_e32 v208, 1.0, v208
	v_add_f32_e32 v209, 1.0, v209
	v_add_f32_e32 v210, 1.0, v210
	v_add_f32_e32 v211, 1.0, v211
	v_add_f32_e32 v212, 1.0, v212
	v_add_f32_e32 v213, 1.0, v213
	v_add_f32_e32 v214, 1.0, v214
	v_add_f32_e32 v215, 1.0, v215
	v_rcp_f32_e32 v208, v208
	v_rcp_f32_e32 v209, v209
	v_rcp_f32_e32 v210, v210
	v_rcp_f32_e32 v211, v211
	v_rcp_f32_e32 v212, v212
	v_rcp_f32_e32 v213, v213
	v_rcp_f32_e32 v214, v214
	v_rcp_f32_e32 v215, v215
	v_cvt_pk_bf16_f32 v156, v208, v209
	v_cvt_pk_bf16_f32 v157, v210, v211
	v_cvt_pk_bf16_f32 v158, v212, v213
	v_cvt_pk_bf16_f32 v159, v214, v215
	ds_bpermute_b32 v246, v217, v156
	ds_bpermute_b32 v247, v217, v157
	ds_bpermute_b32 v248, v217, v158
	ds_bpermute_b32 v249, v217, v159
	v_mul_f32_e32 v208, 0xbfb8aa3b, v70
	v_mul_f32_e32 v209, 0xbfb8aa3b, v71
	v_mul_f32_e32 v210, 0xbfb8aa3b, v72
	v_mul_f32_e32 v211, 0xbfb8aa3b, v73
	v_mul_f32_e32 v212, 0xbfb8aa3b, v66
	v_mul_f32_e32 v213, 0xbfb8aa3b, v67
	v_mul_f32_e32 v214, 0xbfb8aa3b, v68
	v_mul_f32_e32 v215, 0xbfb8aa3b, v69
	v_exp_f32_e32 v208, v208
	v_exp_f32_e32 v209, v209
	v_exp_f32_e32 v210, v210
	v_exp_f32_e32 v211, v211
	v_exp_f32_e32 v212, v212
	v_exp_f32_e32 v213, v213
	v_exp_f32_e32 v214, v214
	v_exp_f32_e32 v215, v215
	v_add_f32_e32 v208, 1.0, v208
	v_add_f32_e32 v209, 1.0, v209
	v_add_f32_e32 v210, 1.0, v210
	v_add_f32_e32 v211, 1.0, v211
	v_add_f32_e32 v212, 1.0, v212
	v_add_f32_e32 v213, 1.0, v213
	v_add_f32_e32 v214, 1.0, v214
	v_add_f32_e32 v215, 1.0, v215
	v_rcp_f32_e32 v208, v208
	v_rcp_f32_e32 v209, v209
	v_rcp_f32_e32 v210, v210
	v_rcp_f32_e32 v211, v211
	v_rcp_f32_e32 v212, v212
	v_rcp_f32_e32 v213, v213
	v_rcp_f32_e32 v214, v214
	v_rcp_f32_e32 v215, v215
	v_cvt_pk_bf16_f32 v160, v208, v209
	v_cvt_pk_bf16_f32 v161, v210, v211
	v_cvt_pk_bf16_f32 v162, v212, v213
	v_cvt_pk_bf16_f32 v163, v214, v215
	ds_bpermute_b32 v250, v217, v160
	ds_bpermute_b32 v251, v217, v161
	ds_bpermute_b32 v252, v217, v162
	ds_bpermute_b32 v253, v217, v163
	s_waitcnt lgkmcnt(0)
	global_store_dwordx4 v235, v[238:241], s[10:11] sc0 sc1
	global_store_dwordx4 v235, v[242:245], s[10:11] offset:256 sc0 sc1
	global_store_dwordx4 v235, v[246:249], s[20:21] sc0 sc1
	global_store_dwordx4 v235, v[250:253], s[20:21] offset:256 sc0 sc1
	s_add_u32 s10, s22, 0x180000
	s_addc_u32 s11, s23, 0
	v_mul_f32_e32 v208, 0xbfb8aa3b, v62
	v_mul_f32_e32 v209, 0xbfb8aa3b, v63
	v_mul_f32_e32 v210, 0xbfb8aa3b, v64
	v_mul_f32_e32 v211, 0xbfb8aa3b, v65
	v_mul_f32_e32 v212, 0xbfb8aa3b, v58
	v_mul_f32_e32 v213, 0xbfb8aa3b, v59
	v_mul_f32_e32 v214, 0xbfb8aa3b, v60
	v_mul_f32_e32 v215, 0xbfb8aa3b, v61
	v_exp_f32_e32 v208, v208
	v_exp_f32_e32 v209, v209
	v_exp_f32_e32 v210, v210
	v_exp_f32_e32 v211, v211
	v_exp_f32_e32 v212, v212
	v_exp_f32_e32 v213, v213
	v_exp_f32_e32 v214, v214
	v_exp_f32_e32 v215, v215
	v_add_f32_e32 v208, 1.0, v208
	v_add_f32_e32 v209, 1.0, v209
	v_add_f32_e32 v210, 1.0, v210
	v_add_f32_e32 v211, 1.0, v211
	v_add_f32_e32 v212, 1.0, v212
	v_add_f32_e32 v213, 1.0, v213
	v_add_f32_e32 v214, 1.0, v214
	v_add_f32_e32 v215, 1.0, v215
	v_rcp_f32_e32 v208, v208
	v_rcp_f32_e32 v209, v209
	v_rcp_f32_e32 v210, v210
	v_rcp_f32_e32 v211, v211
	v_rcp_f32_e32 v212, v212
	v_rcp_f32_e32 v213, v213
	v_rcp_f32_e32 v214, v214
	v_rcp_f32_e32 v215, v215
	v_cvt_pk_bf16_f32 v148, v208, v209
	v_cvt_pk_bf16_f32 v149, v210, v211
	v_cvt_pk_bf16_f32 v150, v212, v213
	v_cvt_pk_bf16_f32 v151, v214, v215
	ds_bpermute_b32 v238, v217, v148
	ds_bpermute_b32 v239, v217, v149
	ds_bpermute_b32 v240, v217, v150
	ds_bpermute_b32 v241, v217, v151
	v_mul_f32_e32 v208, 0xbfb8aa3b, v54
	v_mul_f32_e32 v209, 0xbfb8aa3b, v55
	v_mul_f32_e32 v210, 0xbfb8aa3b, v56
	v_mul_f32_e32 v211, 0xbfb8aa3b, v57
	v_mul_f32_e32 v212, 0xbfb8aa3b, v50
	v_mul_f32_e32 v213, 0xbfb8aa3b, v51
	v_mul_f32_e32 v214, 0xbfb8aa3b, v52
	v_mul_f32_e32 v215, 0xbfb8aa3b, v53
	v_exp_f32_e32 v208, v208
	v_exp_f32_e32 v209, v209
	v_exp_f32_e32 v210, v210
	v_exp_f32_e32 v211, v211
	v_exp_f32_e32 v212, v212
	v_exp_f32_e32 v213, v213
	v_exp_f32_e32 v214, v214
	v_exp_f32_e32 v215, v215
	v_add_f32_e32 v208, 1.0, v208
	v_add_f32_e32 v209, 1.0, v209
	v_add_f32_e32 v210, 1.0, v210
	v_add_f32_e32 v211, 1.0, v211
	v_add_f32_e32 v212, 1.0, v212
	v_add_f32_e32 v213, 1.0, v213
	v_add_f32_e32 v214, 1.0, v214
	v_add_f32_e32 v215, 1.0, v215
	v_rcp_f32_e32 v208, v208
	v_rcp_f32_e32 v209, v209
	v_rcp_f32_e32 v210, v210
	v_rcp_f32_e32 v211, v211
	v_rcp_f32_e32 v212, v212
	v_rcp_f32_e32 v213, v213
	v_rcp_f32_e32 v214, v214
	v_rcp_f32_e32 v215, v215
	v_cvt_pk_bf16_f32 v152, v208, v209
	v_cvt_pk_bf16_f32 v153, v210, v211
	v_cvt_pk_bf16_f32 v154, v212, v213
	v_cvt_pk_bf16_f32 v155, v214, v215
	ds_bpermute_b32 v242, v217, v152
	ds_bpermute_b32 v243, v217, v153
	ds_bpermute_b32 v244, v217, v154
	ds_bpermute_b32 v245, v217, v155
	s_add_u32 s20, s22, 0x1b0000
	s_addc_u32 s21, s23, 0
	v_mul_f32_e32 v208, 0xbfb8aa3b, v46
	v_mul_f32_e32 v209, 0xbfb8aa3b, v47
	v_mul_f32_e32 v210, 0xbfb8aa3b, v48
	v_mul_f32_e32 v211, 0xbfb8aa3b, v49
	v_mul_f32_e32 v212, 0xbfb8aa3b, v42
	v_mul_f32_e32 v213, 0xbfb8aa3b, v43
	v_mul_f32_e32 v214, 0xbfb8aa3b, v44
	v_mul_f32_e32 v215, 0xbfb8aa3b, v45
	v_exp_f32_e32 v208, v208
	v_exp_f32_e32 v209, v209
	v_exp_f32_e32 v210, v210
	v_exp_f32_e32 v211, v211
	v_exp_f32_e32 v212, v212
	v_exp_f32_e32 v213, v213
	v_exp_f32_e32 v214, v214
	v_exp_f32_e32 v215, v215
	v_add_f32_e32 v208, 1.0, v208
	v_add_f32_e32 v209, 1.0, v209
	v_add_f32_e32 v210, 1.0, v210
	v_add_f32_e32 v211, 1.0, v211
	v_add_f32_e32 v212, 1.0, v212
	v_add_f32_e32 v213, 1.0, v213
	v_add_f32_e32 v214, 1.0, v214
	v_add_f32_e32 v215, 1.0, v215
	v_rcp_f32_e32 v208, v208
	v_rcp_f32_e32 v209, v209
	v_rcp_f32_e32 v210, v210
	v_rcp_f32_e32 v211, v211
	v_rcp_f32_e32 v212, v212
	v_rcp_f32_e32 v213, v213
	v_rcp_f32_e32 v214, v214
	v_rcp_f32_e32 v215, v215
	v_cvt_pk_bf16_f32 v156, v208, v209
	v_cvt_pk_bf16_f32 v157, v210, v211
	v_cvt_pk_bf16_f32 v158, v212, v213
	v_cvt_pk_bf16_f32 v159, v214, v215
	ds_bpermute_b32 v246, v217, v156
	ds_bpermute_b32 v247, v217, v157
	ds_bpermute_b32 v248, v217, v158
	ds_bpermute_b32 v249, v217, v159
	v_mul_f32_e32 v208, 0xbfb8aa3b, v38
	v_mul_f32_e32 v209, 0xbfb8aa3b, v39
	v_mul_f32_e32 v210, 0xbfb8aa3b, v40
	v_mul_f32_e32 v211, 0xbfb8aa3b, v41
	v_mul_f32_e32 v212, 0xbfb8aa3b, v34
	v_mul_f32_e32 v213, 0xbfb8aa3b, v35
	v_mul_f32_e32 v214, 0xbfb8aa3b, v36
	v_mul_f32_e32 v215, 0xbfb8aa3b, v37
	v_exp_f32_e32 v208, v208
	v_exp_f32_e32 v209, v209
	v_exp_f32_e32 v210, v210
	v_exp_f32_e32 v211, v211
	v_exp_f32_e32 v212, v212
	v_exp_f32_e32 v213, v213
	v_exp_f32_e32 v214, v214
	v_exp_f32_e32 v215, v215
	v_add_f32_e32 v208, 1.0, v208
	v_add_f32_e32 v209, 1.0, v209
	v_add_f32_e32 v210, 1.0, v210
	v_add_f32_e32 v211, 1.0, v211
	v_add_f32_e32 v212, 1.0, v212
	v_add_f32_e32 v213, 1.0, v213
	v_add_f32_e32 v214, 1.0, v214
	v_add_f32_e32 v215, 1.0, v215
	v_rcp_f32_e32 v208, v208
	v_rcp_f32_e32 v209, v209
	v_rcp_f32_e32 v210, v210
	v_rcp_f32_e32 v211, v211
	v_rcp_f32_e32 v212, v212
	v_rcp_f32_e32 v213, v213
	v_rcp_f32_e32 v214, v214
	v_rcp_f32_e32 v215, v215
	v_cvt_pk_bf16_f32 v160, v208, v209
	v_cvt_pk_bf16_f32 v161, v210, v211
	v_cvt_pk_bf16_f32 v162, v212, v213
	v_cvt_pk_bf16_f32 v163, v214, v215
	ds_bpermute_b32 v250, v217, v160
	ds_bpermute_b32 v251, v217, v161
	ds_bpermute_b32 v252, v217, v162
	ds_bpermute_b32 v253, v217, v163
	s_waitcnt lgkmcnt(0)
	global_store_dwordx4 v235, v[238:241], s[10:11] sc0 sc1
	global_store_dwordx4 v235, v[242:245], s[10:11] offset:256 sc0 sc1
	global_store_dwordx4 v235, v[246:249], s[20:21] sc0 sc1
	global_store_dwordx4 v235, v[250:253], s[20:21] offset:256 sc0 sc1
	s_add_u32 s10, s22, 0x1e0000
	s_addc_u32 s11, s23, 0
	v_mul_f32_e32 v208, 0xbfb8aa3b, v28
	v_mul_f32_e32 v209, 0xbfb8aa3b, v29
	v_mul_f32_e32 v210, 0xbfb8aa3b, v30
	v_mul_f32_e32 v211, 0xbfb8aa3b, v31
	v_mul_f32_e32 v212, 0xbfb8aa3b, v24
	v_mul_f32_e32 v213, 0xbfb8aa3b, v25
	v_mul_f32_e32 v214, 0xbfb8aa3b, v26
	v_mul_f32_e32 v215, 0xbfb8aa3b, v27
	v_exp_f32_e32 v208, v208
	v_exp_f32_e32 v209, v209
	v_exp_f32_e32 v210, v210
	v_exp_f32_e32 v211, v211
	v_exp_f32_e32 v212, v212
	v_exp_f32_e32 v213, v213
	v_exp_f32_e32 v214, v214
	v_exp_f32_e32 v215, v215
	v_add_f32_e32 v208, 1.0, v208
	v_add_f32_e32 v209, 1.0, v209
	v_add_f32_e32 v210, 1.0, v210
	v_add_f32_e32 v211, 1.0, v211
	v_add_f32_e32 v212, 1.0, v212
	v_add_f32_e32 v213, 1.0, v213
	v_add_f32_e32 v214, 1.0, v214
	v_add_f32_e32 v215, 1.0, v215
	v_rcp_f32_e32 v208, v208
	v_rcp_f32_e32 v209, v209
	v_rcp_f32_e32 v210, v210
	v_rcp_f32_e32 v211, v211
	v_rcp_f32_e32 v212, v212
	v_rcp_f32_e32 v213, v213
	v_rcp_f32_e32 v214, v214
	v_rcp_f32_e32 v215, v215
	v_cvt_pk_bf16_f32 v148, v208, v209
	v_cvt_pk_bf16_f32 v149, v210, v211
	v_cvt_pk_bf16_f32 v150, v212, v213
	v_cvt_pk_bf16_f32 v151, v214, v215
	ds_bpermute_b32 v238, v217, v148
	ds_bpermute_b32 v239, v217, v149
	ds_bpermute_b32 v240, v217, v150
	ds_bpermute_b32 v241, v217, v151
	v_mul_f32_e32 v208, 0xbfb8aa3b, v20
	v_mul_f32_e32 v209, 0xbfb8aa3b, v21
	v_mul_f32_e32 v210, 0xbfb8aa3b, v22
	v_mul_f32_e32 v211, 0xbfb8aa3b, v23
	v_mul_f32_e32 v212, 0xbfb8aa3b, v16
	v_mul_f32_e32 v213, 0xbfb8aa3b, v17
	v_mul_f32_e32 v214, 0xbfb8aa3b, v18
	v_mul_f32_e32 v215, 0xbfb8aa3b, v19
	v_exp_f32_e32 v208, v208
	v_exp_f32_e32 v209, v209
	v_exp_f32_e32 v210, v210
	v_exp_f32_e32 v211, v211
	v_exp_f32_e32 v212, v212
	v_exp_f32_e32 v213, v213
	v_exp_f32_e32 v214, v214
	v_exp_f32_e32 v215, v215
	v_add_f32_e32 v208, 1.0, v208
	v_add_f32_e32 v209, 1.0, v209
	v_add_f32_e32 v210, 1.0, v210
	v_add_f32_e32 v211, 1.0, v211
	v_add_f32_e32 v212, 1.0, v212
	v_add_f32_e32 v213, 1.0, v213
	v_add_f32_e32 v214, 1.0, v214
	v_add_f32_e32 v215, 1.0, v215
	v_rcp_f32_e32 v208, v208
	v_rcp_f32_e32 v209, v209
	v_rcp_f32_e32 v210, v210
	v_rcp_f32_e32 v211, v211
	v_rcp_f32_e32 v212, v212
	v_rcp_f32_e32 v213, v213
	v_rcp_f32_e32 v214, v214
	v_rcp_f32_e32 v215, v215
	v_cvt_pk_bf16_f32 v152, v208, v209
	v_cvt_pk_bf16_f32 v153, v210, v211
	v_cvt_pk_bf16_f32 v154, v212, v213
	v_cvt_pk_bf16_f32 v155, v214, v215
	ds_bpermute_b32 v242, v217, v152
	ds_bpermute_b32 v243, v217, v153
	ds_bpermute_b32 v244, v217, v154
	ds_bpermute_b32 v245, v217, v155
	s_add_u32 s20, s22, 0x210000
	s_addc_u32 s21, s23, 0
	v_mul_f32_e32 v208, 0xbfb8aa3b, v12
	v_mul_f32_e32 v209, 0xbfb8aa3b, v13
	v_mul_f32_e32 v210, 0xbfb8aa3b, v14
	v_mul_f32_e32 v211, 0xbfb8aa3b, v15
	v_mul_f32_e32 v212, 0xbfb8aa3b, v8
	v_mul_f32_e32 v213, 0xbfb8aa3b, v9
	v_mul_f32_e32 v214, 0xbfb8aa3b, v10
	v_mul_f32_e32 v215, 0xbfb8aa3b, v11
	v_exp_f32_e32 v208, v208
	v_exp_f32_e32 v209, v209
	v_exp_f32_e32 v210, v210
	v_exp_f32_e32 v211, v211
	v_exp_f32_e32 v212, v212
	v_exp_f32_e32 v213, v213
	v_exp_f32_e32 v214, v214
	v_exp_f32_e32 v215, v215
	v_add_f32_e32 v208, 1.0, v208
	v_add_f32_e32 v209, 1.0, v209
	v_add_f32_e32 v210, 1.0, v210
	v_add_f32_e32 v211, 1.0, v211
	v_add_f32_e32 v212, 1.0, v212
	v_add_f32_e32 v213, 1.0, v213
	v_add_f32_e32 v214, 1.0, v214
	v_add_f32_e32 v215, 1.0, v215
	v_rcp_f32_e32 v208, v208
	v_rcp_f32_e32 v209, v209
	v_rcp_f32_e32 v210, v210
	v_rcp_f32_e32 v211, v211
	v_rcp_f32_e32 v212, v212
	v_rcp_f32_e32 v213, v213
	v_rcp_f32_e32 v214, v214
	v_rcp_f32_e32 v215, v215
	v_cvt_pk_bf16_f32 v156, v208, v209
	v_cvt_pk_bf16_f32 v157, v210, v211
	v_cvt_pk_bf16_f32 v158, v212, v213
	v_cvt_pk_bf16_f32 v159, v214, v215
	ds_bpermute_b32 v246, v217, v156
	ds_bpermute_b32 v247, v217, v157
	ds_bpermute_b32 v248, v217, v158
	ds_bpermute_b32 v249, v217, v159
	v_mul_f32_e32 v208, 0xbfb8aa3b, v4
	v_mul_f32_e32 v209, 0xbfb8aa3b, v5
	v_mul_f32_e32 v210, 0xbfb8aa3b, v6
	v_mul_f32_e32 v211, 0xbfb8aa3b, v7
	v_mul_f32_e32 v212, 0xbfb8aa3b, v0
	v_mul_f32_e32 v213, 0xbfb8aa3b, v1
	v_mul_f32_e32 v214, 0xbfb8aa3b, v2
	v_mul_f32_e32 v215, 0xbfb8aa3b, v3
	v_exp_f32_e32 v208, v208
	v_exp_f32_e32 v209, v209
	v_exp_f32_e32 v210, v210
	v_exp_f32_e32 v211, v211
	v_exp_f32_e32 v212, v212
	v_exp_f32_e32 v213, v213
	v_exp_f32_e32 v214, v214
	v_exp_f32_e32 v215, v215
	v_add_f32_e32 v208, 1.0, v208
	v_add_f32_e32 v209, 1.0, v209
	v_add_f32_e32 v210, 1.0, v210
	v_add_f32_e32 v211, 1.0, v211
	v_add_f32_e32 v212, 1.0, v212
	v_add_f32_e32 v213, 1.0, v213
	v_add_f32_e32 v214, 1.0, v214
	v_add_f32_e32 v215, 1.0, v215
	v_rcp_f32_e32 v208, v208
	v_rcp_f32_e32 v209, v209
	v_rcp_f32_e32 v210, v210
	v_rcp_f32_e32 v211, v211
	v_rcp_f32_e32 v212, v212
	v_rcp_f32_e32 v213, v213
	v_rcp_f32_e32 v214, v214
	v_rcp_f32_e32 v215, v215
	v_cvt_pk_bf16_f32 v160, v208, v209
	v_cvt_pk_bf16_f32 v161, v210, v211
	v_cvt_pk_bf16_f32 v162, v212, v213
	v_cvt_pk_bf16_f32 v163, v214, v215
	ds_bpermute_b32 v250, v217, v160
	ds_bpermute_b32 v251, v217, v161
	ds_bpermute_b32 v252, v217, v162
	ds_bpermute_b32 v253, v217, v163
	s_waitcnt lgkmcnt(0)
	global_store_dwordx4 v235, v[238:241], s[10:11] sc0 sc1
	global_store_dwordx4 v235, v[242:245], s[10:11] offset:256 sc0 sc1
	global_store_dwordx4 v235, v[246:249], s[20:21] sc0 sc1
	global_store_dwordx4 v235, v[250:253], s[20:21] offset:256 sc0 sc1
	s_branch .Lmain_latch_fast
